# grid barrier: group leaders bump all 8 per-group copies of the arrival counter, members poll their group's copy (one hop less than leader->global->flag)
# speedup vs baseline: 1.0584x; 1.0063x over previous
; DI void grid_barrier(unsigned* ctr, unsigned target) {
;   __syncthreads();
;   if (threadIdx.x == 0) {
;     __threadfence();
;     __hip_atomic_fetch_add(ctr, 1u, __ATOMIC_RELAXED, __HIP_MEMORY_SCOPE_AGENT);
;     unsigned spins = 0;
;     while (__hip_atomic_load(ctr, __ATOMIC_RELAXED, __HIP_MEMORY_SCOPE_AGENT) < target && spins < (1u << 26)) { __builtin_amdgcn_s_sleep(2); ++spins; }
;     __threadfence();
;   }
;   __syncthreads();
; }
.LBB0_871:
	s_mov_b64 s[10:11], 0
	s_andn2_b64 vcc, exec, s[14:15]
	v_readlane_b32 s4, v254, 33
	s_cbranch_vccnz .LBB0_881
	v_readlane_b32 s4, v254, 33
	s_add_i32 s4, s4, 1
	s_waitcnt vmcnt(0) lgkmcnt(0)
	s_barrier
	s_mov_b64 s[8:9], exec
	v_readlane_b32 s10, v254, 36
	v_readlane_b32 s11, v254, 37
	s_and_b64 s[10:11], s[8:9], s[10:11]
	s_mov_b64 exec, s[10:11]
	s_cbranch_execz .LBB0_879
	buffer_wbl2 sc1
	v_readlane_b32 s24, v253, 5
	v_readlane_b32 s25, v253, 6
	v_readlane_b32 s10, v254, 1
	s_and_b32 s10, s10, 7
	s_sub_u32 s11, s33, s10
	s_add_u32 s11, s11, 7
	s_lshr_b32 s11, s11, 3
	s_mul_i32 s11, s11, s4
	s_lshl_b32 s10, s10, 7
	s_add_u32 s22, s24, s10
	s_addc_u32 s23, s25, 0
	s_add_u32 s14, s24, 0x500
	s_addc_u32 s15, s25, 0
	v_mov_b32_e32 v0, 1
	s_waitcnt vmcnt(0)
	global_atomic_add v1, v131, v0, s[22:23] offset:256 sc0
	s_waitcnt vmcnt(0)
	v_add_u32_e32 v1, 1, v1
	v_cmp_eq_u32_e32 vcc, s11, v1
	s_mov_b32 s10, 0
	s_cbranch_vccz .Lgb_wait
	global_atomic_add v131, v0, s[24:25] offset:-1792
	global_atomic_add v131, v0, s[24:25] offset:-1664
	global_atomic_add v131, v0, s[24:25] offset:-1536
	global_atomic_add v131, v0, s[24:25] offset:-1408
	global_atomic_add v131, v0, s[24:25] offset:-1280
	global_atomic_add v131, v0, s[24:25] offset:-1152
	global_atomic_add v131, v0, s[24:25] offset:-1024
	global_atomic_add v131, v0, s[24:25] offset:-896
.Lgb_wait:
	s_min_u32 s11, s33, 8
	s_mul_i32 s11, s11, s4
.Lgb_lp:
	global_load_dword v1, v131, s[22:23] offset:-1792 sc1
	s_add_u32 s10, s10, 1
	s_waitcnt vmcnt(0)
	v_cmp_gt_u32_e32 vcc, s11, v1
	s_cbranch_vccz .Lgb_done
	s_cmp_lt_u32 s10, 0x400000
	s_cbranch_scc1 .Lgb_lp
